# trailing wave half's re-offset barrier moved behind its next-unit set-up (set-up overlaps the leading half's)
# baseline (speedup 1.0000x reference)
_Z10fwd_kernel4Args:
	s_mov_b32 s100, 0
	s_mov_b32 s99, 0
	s_load_dwordx8 s[20:27], s[0:1], 0xc0
	s_load_dword s33, s[0:1], 0xe0
	v_and_b32_e32 v1, 0x3ff, v0
	s_add_u32 s6, s0, 0xd8
	v_readfirstlane_b32 s10, v1
	v_mbcnt_lo_u32_b32 v2, -1, 0
	s_addc_u32 s7, s1, 0
	v_mbcnt_hi_u32_b32 v152, -1, v2
	s_and_b32 s3, s10, 0xffffffc0
	v_add_u32_e32 v153, s3, v152
	v_cmp_gt_i32_e32 vcc, 2, v153
	s_and_saveexec_b64 s[4:5], vcc
	v_lshl_add_u32 v2, v153, 2, 0
	v_add_u32_e32 v2, 0x20040, v2
	v_mov_b32_e32 v3, 0
	ds_write_b32 v2, v3
	s_or_b64 exec, exec, s[4:5]
	s_waitcnt lgkmcnt(0)
	s_sub_u32 s101, s26, 1
	s_sub_u32 s101, s101, s2
	s_barrier
	s_getreg_b32 s3, hwreg(HW_REG_XCC_ID, 0, 4)
	s_and_b32 s96, s3, 15
	v_cmp_eq_u32_e64 s[4:5], 0, v152
	s_cmp_lt_u32 s10, 64
	s_cselect_b64 s[8:9], -1, 0
	v_writelane_b32 v254, s4, 0
	s_nop 1
	v_writelane_b32 v254, s5, 1
	v_writelane_b32 v254, s8, 2
	s_and_b64 s[92:93], s[8:9], s[4:5]
	s_nop 0
	v_writelane_b32 v254, s9, 3
	s_and_saveexec_b64 s[4:5], s[92:93]
	s_cbranch_execz .LBB0_5
	s_mov_b64 s[12:13], exec
	v_mbcnt_lo_u32_b32 v2, s12, 0
	v_mbcnt_hi_u32_b32 v2, s13, v2
	v_cmp_eq_u32_e32 vcc, 0, v2
	s_and_b64 s[8:9], exec, vcc
	s_mov_b64 exec, s[8:9]
	s_cbranch_execz .LBB0_5
	s_lshl_b32 s3, s96, 8
	s_bcnt1_i32_b64 s8, s[12:13]
	v_mov_b32_e32 v2, s3
	v_mov_b32_e32 v3, s8
	global_atomic_add v2, v3, s[24:25] offset:1024

.LBB0_109:
	s_ashr_i32 s89, s88, 31
	s_lshl_b64 s[8:9], s[88:89], 19
	s_add_u32 s90, s30, s8
	s_addc_u32 s91, s31, s9
	s_and_b64 s[8:9], s[0:1], exec
	s_cselect_b32 s7, s91, s39
	s_cselect_b32 s16, s90, s38
	s_ashr_i32 s87, s86, 31
	s_lshl_b64 s[8:9], s[86:87], 19
	s_add_u32 s92, s3, s8
	s_addc_u32 s93, s44, s9
	s_and_b64 s[8:9], s[0:1], exec
	s_cselect_b32 s17, s93, s37
	s_cselect_b32 s18, s92, s36
	s_add_u32 s94, s38, 0x40080
	s_addc_u32 s95, s39, 0
	s_add_u32 s28, s36, 0x100
	v_mov_b32_e32 v0, 0
	s_addc_u32 s29, s37, 0
	s_mov_b32 s42, -2
	v_mov_b32_e32 v156, 0
	v_mov_b32_e32 v157, 0
	v_mov_b32_e32 v158, 0
	v_mov_b32_e32 v159, 0
	s_nop 1
	v_mfma_f32_32x32x16_bf16 v[0:15], v[156:159], v[156:159], 0
	v_mfma_f32_32x32x16_bf16 v[16:31], v[156:159], v[156:159], 0
	v_mfma_f32_32x32x16_bf16 v[32:47], v[156:159], v[156:159], 0
	v_mfma_f32_32x32x16_bf16 v[48:63], v[156:159], v[156:159], 0
	v_mfma_f32_32x32x16_bf16 v[64:79], v[156:159], v[156:159], 0
	v_mfma_f32_32x32x16_bf16 v[80:95], v[156:159], v[156:159], 0
	v_mfma_f32_32x32x16_bf16 v[96:111], v[156:159], v[156:159], 0
	v_mfma_f32_32x32x16_bf16 v[112:127], v[156:159], v[156:159], 0
	s_cmp_eq_u32 s100, 1
	s_cbranch_scc0 .Lbm_rg
	s_mov_b32 s100, 0
	s_barrier
.Lbm_rg:
.LBB0_110:
	ds_read_b128 v[156:159], v150
	ds_read_b128 v[160:163], v150 offset:1024
	ds_read_b128 v[164:167], v150 offset:2048
	ds_read_b128 v[168:171], v150 offset:3072
	ds_read_b128 v[172:175], v151
	ds_read_b128 v[184:187], v151 offset:1024
	ds_read_b128 v[188:191], v151 offset:2048
	ds_read_b128 v[192:195], v151 offset:3072
	s_add_u32 s8, s94, 0xfffc0080
	s_addc_u32 s9, s95, -1
	s_cmp_eq_u32 s42, 12
	s_cselect_b32 s39, s7, s9
	s_cselect_b32 s38, s16, s8
	s_cselect_b32 s37, s17, s29
	s_cselect_b32 s36, s18, s28
	v_lshl_add_u64 v[146:147], s[94:95], 0, v[138:139]
	s_add_i32 m0, s15, 0xc000
	ds_read_b128 v[196:199], v154
	ds_read_b128 v[200:203], v154 offset:1024
	ds_read_b128 v[204:207], v154 offset:2048
	ds_read_b128 v[208:211], v154 offset:3072
	ds_read_b128 v[212:215], v154 offset:4096
	ds_read_b128 v[216:219], v154 offset:5120
	ds_read_b128 v[220:223], v154 offset:6144
	ds_read_b128 v[224:227], v154 offset:7168
	global_load_lds_dwordx4 v[146:147], off
	v_lshl_add_u64 v[146:147], s[94:95], 0, v[140:141]
	s_add_i32 m0, s15, 0xe000
	s_nop 0
	global_load_lds_dwordx4 v[146:147], off
	s_cmp_eq_u32 s99, 0
	s_cbranch_scc1 .Ldpw_0_0a
	s_waitcnt vmcnt(16)
	s_branch .Ldpw_0_0b

.Ldpw_0_1b:
	s_waitcnt lgkmcnt(0)
	s_barrier
	s_setprio 1
	s_waitcnt lgkmcnt(0)
	v_mfma_f32_16x16x32_bf16 v[60:63], v[156:159], v[196:199], v[60:63]
	v_mfma_f32_16x16x32_bf16 v[56:59], v[164:167], v[196:199], v[56:59]
	v_mfma_f32_16x16x32_bf16 v[44:47], v[156:159], v[204:207], v[44:47]
	v_mfma_f32_16x16x32_bf16 v[40:43], v[164:167], v[204:207], v[40:43]
	v_mfma_f32_16x16x32_bf16 v[28:31], v[156:159], v[212:215], v[28:31]
	v_mfma_f32_16x16x32_bf16 v[24:27], v[164:167], v[212:215], v[24:27]
	v_mfma_f32_16x16x32_bf16 v[12:15], v[156:159], v[220:223], v[12:15]
	v_mfma_f32_16x16x32_bf16 v[8:11], v[164:167], v[220:223], v[8:11]
	v_mfma_f32_16x16x32_bf16 v[60:63], v[160:163], v[200:203], v[60:63]
	v_mfma_f32_16x16x32_bf16 v[56:59], v[168:171], v[200:203], v[56:59]
	v_mfma_f32_16x16x32_bf16 v[44:47], v[160:163], v[208:211], v[44:47]
	v_mfma_f32_16x16x32_bf16 v[40:43], v[168:171], v[208:211], v[40:43]
	v_mfma_f32_16x16x32_bf16 v[28:31], v[160:163], v[216:219], v[28:31]
	v_mfma_f32_16x16x32_bf16 v[24:27], v[168:171], v[216:219], v[24:27]
	v_mfma_f32_16x16x32_bf16 v[12:15], v[160:163], v[224:227], v[12:15]
	v_mfma_f32_16x16x32_bf16 v[8:11], v[168:171], v[224:227], v[8:11]
	s_setprio 0
	s_setprio 1
	v_mfma_f32_16x16x32_bf16 v[52:55], v[172:175], v[196:199], v[52:55]
	v_mfma_f32_16x16x32_bf16 v[48:51], v[188:191], v[196:199], v[48:51]
	v_mfma_f32_16x16x32_bf16 v[36:39], v[172:175], v[204:207], v[36:39]
	v_mfma_f32_16x16x32_bf16 v[32:35], v[188:191], v[204:207], v[32:35]
	v_mfma_f32_16x16x32_bf16 v[20:23], v[172:175], v[212:215], v[20:23]
	v_mfma_f32_16x16x32_bf16 v[16:19], v[188:191], v[212:215], v[16:19]
	v_mfma_f32_16x16x32_bf16 v[4:7], v[172:175], v[220:223], v[4:7]
	v_mfma_f32_16x16x32_bf16 v[0:3], v[188:191], v[220:223], v[0:3]
	v_mfma_f32_16x16x32_bf16 v[52:55], v[184:187], v[200:203], v[52:55]
	v_mfma_f32_16x16x32_bf16 v[48:51], v[192:195], v[200:203], v[48:51]
	v_mfma_f32_16x16x32_bf16 v[36:39], v[184:187], v[208:211], v[36:39]
	v_mfma_f32_16x16x32_bf16 v[32:35], v[192:195], v[208:211], v[32:35]
	v_mfma_f32_16x16x32_bf16 v[20:23], v[184:187], v[216:219], v[20:23]
	v_mfma_f32_16x16x32_bf16 v[16:19], v[192:195], v[216:219], v[16:19]
	v_mfma_f32_16x16x32_bf16 v[4:7], v[184:187], v[224:227], v[4:7]
	v_mfma_f32_16x16x32_bf16 v[0:3], v[192:195], v[224:227], v[0:3]
	s_setprio 0
	s_barrier
	s_add_i32 s43, 0, 0x18000
	v_add_u32_e32 v155, s43, v149
	s_add_i32 s77, 0, 0x1c000
	ds_read_b128 v[156:159], v155
	ds_read_b128 v[160:163], v155 offset:1024
	ds_read_b128 v[164:167], v155 offset:2048
	ds_read_b128 v[168:171], v155 offset:3072
	v_add_u32_e32 v155, s77, v149
	ds_read_b128 v[172:175], v155
	ds_read_b128 v[184:187], v155 offset:1024
	ds_read_b128 v[188:191], v155 offset:2048
	ds_read_b128 v[192:195], v155 offset:3072
	s_add_u32 s8, s38, 0x40000
	s_addc_u32 s9, s39, 0
	s_mov_b32 m0, s49
	v_lshl_add_u64 v[234:235], s[8:9], 0, v[128:129]
	ds_read_b128 v[196:199], v154 offset:32768
	ds_read_b128 v[200:203], v154 offset:33792
	ds_read_b128 v[204:207], v154 offset:34816
	ds_read_b128 v[208:211], v154 offset:35840
	ds_read_b128 v[212:215], v154 offset:36864
	ds_read_b128 v[216:219], v154 offset:37888
	ds_read_b128 v[220:223], v154 offset:38912
	ds_read_b128 v[224:227], v154 offset:39936
	global_load_lds_dwordx4 v[234:235], off
	v_lshl_add_u64 v[234:235], s[8:9], 0, v[132:133]
	s_mov_b32 m0, s68
	s_nop 0
	global_load_lds_dwordx4 v[234:235], off
	s_waitcnt vmcnt(8)
	s_cmp_eq_u32 s99, 0
	s_cbranch_scc1 .Ldp_0_l
	v_readlane_b32 s100, v0, 0
	s_mov_b64 exec, 1
	v_writelane_b32 v0, 1, 0
	s_nop 1
	global_atomic_add v0, v0, s[98:99]
	s_nop 1
	v_writelane_b32 v0, s100, 0
	s_mov_b64 exec, -1
	s_mov_b32 s99, 0
	s_mov_b32 s100, 0

.LBB0_148:
	s_or_b64 exec, exec, s[6:7]
	s_andn2_b64 vcc, exec, s[0:1]
	s_mov_b64 s[0:1], -1
	s_cbranch_vccnz .LBB0_106
	s_andn2_b64 vcc, exec, s[40:41]
	s_cbranch_vccnz .LBB0_105
	s_mov_b32 s100, 1
	s_branch .LBB0_105
.LBB0_151:
	s_waitcnt vmcnt(0)
	s_cmp_eq_u32 s99, 0
	s_cbranch_scc1 .Ldp_0_x
	v_readlane_b32 s100, v0, 0
	s_mov_b64 exec, 1
	v_writelane_b32 v0, 1, 0
	s_nop 1
	global_atomic_add v0, v0, s[98:99]
	s_nop 1
	v_writelane_b32 v0, s100, 0
	s_mov_b64 exec, -1
	s_mov_b32 s99, 0
	s_mov_b32 s100, 0

.Lgmap_done:
.LBB0_457:
	s_ashr_i32 s57, s56, 31
	s_lshl_b64 s[8:9], s[56:57], 19
	s_add_u32 s1, s30, s8
	s_addc_u32 s16, s31, s9
	s_ashr_i32 s8, s46, 1
	s_ashr_i32 s9, s8, 31
	s_lshl_b64 s[8:9], s[8:9], 9
	s_add_u32 s72, s1, s8
	s_addc_u32 s73, s16, s9
	s_and_b64 s[8:9], s[44:45], exec
	s_cselect_b32 s1, s73, s83
	s_cselect_b32 s16, s72, s82
	s_ashr_i32 s47, s46, 31
	s_lshl_b64 s[8:9], s[46:47], 17
	s_add_u32 s74, s3, s8
	s_addc_u32 s75, s27, s9
	s_and_b64 s[8:9], s[44:45], exec
	v_mov_b32_e32 v0, 0
	s_cselect_b32 s17, s75, s81
	s_cselect_b32 s28, s74, s80
	s_mov_b32 s18, 0
	s_mov_b64 s[84:85], -1
	s_mov_b64 s[36:37], 0
	v_mov_b32_e32 v28, 0
	v_mov_b32_e32 v29, 0
	v_mov_b32_e32 v30, 0
	v_mov_b32_e32 v31, 0
	s_nop 1
	v_mfma_f32_16x16x32_bf16 v[0:3], v[28:31], v[28:31], 0
	v_mfma_f32_16x16x32_bf16 v[4:7], v[28:31], v[28:31], 0
	v_mfma_f32_16x16x32_bf16 v[8:11], v[28:31], v[28:31], 0
	v_mfma_f32_16x16x32_bf16 v[12:15], v[28:31], v[28:31], 0
	v_mfma_f32_16x16x32_bf16 v[16:19], v[28:31], v[28:31], 0
	v_mfma_f32_16x16x32_bf16 v[20:23], v[28:31], v[28:31], 0
	v_mfma_f32_16x16x32_bf16 v[24:27], v[28:31], v[28:31], 0
	v_mfma_f32_16x16x32_bf16 v[36:39], v[28:31], v[28:31], 0
	v_mfma_f32_16x16x32_bf16 v[48:51], v[28:31], v[28:31], 0
	v_mfma_f32_16x16x32_bf16 v[52:55], v[28:31], v[28:31], 0
	v_mfma_f32_16x16x32_bf16 v[56:59], v[28:31], v[28:31], 0
	v_mfma_f32_16x16x32_bf16 v[60:63], v[28:31], v[28:31], 0
	v_mfma_f32_16x16x32_bf16 v[64:67], v[28:31], v[28:31], 0
	v_mfma_f32_16x16x32_bf16 v[68:71], v[28:31], v[28:31], 0
	v_mfma_f32_16x16x32_bf16 v[72:75], v[28:31], v[28:31], 0
	v_mfma_f32_16x16x32_bf16 v[76:79], v[28:31], v[28:31], 0
	v_mfma_f32_16x16x32_bf16 v[80:83], v[28:31], v[28:31], 0
	v_mfma_f32_16x16x32_bf16 v[84:87], v[28:31], v[28:31], 0
	v_mfma_f32_16x16x32_bf16 v[88:91], v[28:31], v[28:31], 0
	v_mfma_f32_16x16x32_bf16 v[92:95], v[28:31], v[28:31], 0
	v_mfma_f32_16x16x32_bf16 v[96:99], v[28:31], v[28:31], 0
	v_mfma_f32_16x16x32_bf16 v[100:103], v[28:31], v[28:31], 0
	v_mfma_f32_16x16x32_bf16 v[104:107], v[28:31], v[28:31], 0
	v_mfma_f32_16x16x32_bf16 v[108:111], v[28:31], v[28:31], 0
	v_mfma_f32_16x16x32_bf16 v[112:115], v[28:31], v[28:31], 0
	v_mfma_f32_16x16x32_bf16 v[116:119], v[28:31], v[28:31], 0
	v_mfma_f32_16x16x32_bf16 v[120:123], v[28:31], v[28:31], 0
	v_mfma_f32_16x16x32_bf16 v[124:127], v[28:31], v[28:31], 0
	v_mfma_f32_16x16x32_bf16 v[128:131], v[28:31], v[28:31], 0
	v_mfma_f32_16x16x32_bf16 v[132:135], v[28:31], v[28:31], 0
	v_mfma_f32_16x16x32_bf16 v[136:139], v[28:31], v[28:31], 0
	v_mfma_f32_16x16x32_bf16 v[140:143], v[28:31], v[28:31], 0
	s_cmp_eq_u32 s100, 1
	s_cbranch_scc0 .Lbm_ga
	s_mov_b32 s100, 0
	s_barrier
.Lbm_ga:
.LBB0_458:
	s_add_u32 s19, s82, s18
	s_addc_u32 s29, s83, 0
	s_add_u32 s38, s19, 0x100
	s_addc_u32 s39, s29, 0
	s_and_b64 s[8:9], s[36:37], exec
	s_cselect_b32 s49, s1, s39
	s_cselect_b32 s48, s16, s38
	s_add_u32 s8, s80, s18
	s_addc_u32 s9, s81, 0
	s_add_u32 s18, s8, 0x100
	s_addc_u32 s38, s9, 0
	s_and_b64 s[8:9], s[36:37], exec
	s_cselect_b32 s51, s17, s38
	s_cselect_b32 s50, s28, s18
	s_add_u32 s70, s19, 0x40080
	s_addc_u32 s71, s29, 0
	s_add_i32 vcc_hi, s91, s33
	ds_read_b128 v[28:31], v173
	ds_read_b128 v[32:35], v173 offset:1024
	ds_read_b128 v[40:43], v173 offset:2048
	ds_read_b128 v[44:47], v173 offset:3072
	ds_read_b128 v[144:147], v174
	ds_read_b128 v[148:151], v174 offset:1024
	ds_read_b128 v[166:169], v174 offset:2048
	ds_read_b128 v[188:191], v174 offset:3072
	s_add_i32 m0, s41, 0xc000
	s_add_i32 s76, s41, 0xe000
	s_add_i32 s97, vcc_hi, 0x2000
	s_add_u32 s68, s50, 0x10000
	s_addc_u32 s69, s51, 0
	s_add_i32 s9, s92, s33
	s_add_i32 s8, s9, 0x2000
	s_add_i32 vcc_lo, 0, 0x18000
	s_add_i32 s57, 0, 0x1c000
	s_add_u32 s38, s48, 0x40000
	s_addc_u32 s39, s49, 0
	s_add_i32 s47, vcc_lo, s33
	s_add_i32 s19, s47, 0x2000
	s_add_u32 s36, s50, 0x10080
	s_addc_u32 s37, s51, 0
	s_add_i32 s29, s57, s33
	s_add_i32 s18, s29, 0x2000
	v_lshl_add_u64 v[224:225], s[70:71], 0, v[160:161]
	ds_read_b128 v[192:195], v175
	ds_read_b128 v[196:199], v175 offset:1024
	ds_read_b128 v[200:203], v175 offset:2048
	ds_read_b128 v[204:207], v175 offset:3072
	ds_read_b128 v[208:211], v175 offset:4096
	ds_read_b128 v[212:215], v175 offset:5120
	ds_read_b128 v[216:219], v175 offset:6144
	ds_read_b128 v[220:223], v175 offset:7168
	global_load_lds_dwordx4 v[224:225], off
	v_lshl_add_u64 v[224:225], s[70:71], 0, v[156:157]
	s_mov_b32 m0, s76
	s_nop 0
	global_load_lds_dwordx4 v[224:225], off
	s_cmp_eq_u32 s99, 0
	s_cbranch_scc1 .Ldpw_1_0a
	s_waitcnt vmcnt(16)
	s_branch .Ldpw_1_0b

.Ldpw_1_1b:
	s_waitcnt lgkmcnt(0)
	s_barrier
	s_setprio 1
	s_waitcnt lgkmcnt(0)
	v_mfma_f32_16x16x32_bf16 v[76:79], v[28:31], v[192:195], v[76:79]
	v_mfma_f32_16x16x32_bf16 v[68:71], v[40:43], v[192:195], v[68:71]
	v_mfma_f32_16x16x32_bf16 v[60:63], v[28:31], v[200:203], v[60:63]
	v_mfma_f32_16x16x32_bf16 v[52:55], v[40:43], v[200:203], v[52:55]
	v_mfma_f32_16x16x32_bf16 v[36:39], v[28:31], v[208:211], v[36:39]
	v_mfma_f32_16x16x32_bf16 v[20:23], v[40:43], v[208:211], v[20:23]
	v_mfma_f32_16x16x32_bf16 v[12:15], v[28:31], v[216:219], v[12:15]
	v_mfma_f32_16x16x32_bf16 v[4:7], v[40:43], v[216:219], v[4:7]
	v_mfma_f32_16x16x32_bf16 v[76:79], v[32:35], v[196:199], v[76:79]
	v_mfma_f32_16x16x32_bf16 v[68:71], v[44:47], v[196:199], v[68:71]
	v_mfma_f32_16x16x32_bf16 v[60:63], v[32:35], v[204:207], v[60:63]
	v_mfma_f32_16x16x32_bf16 v[52:55], v[44:47], v[204:207], v[52:55]
	v_mfma_f32_16x16x32_bf16 v[36:39], v[32:35], v[212:215], v[36:39]
	v_mfma_f32_16x16x32_bf16 v[20:23], v[44:47], v[212:215], v[20:23]
	v_mfma_f32_16x16x32_bf16 v[12:15], v[32:35], v[220:223], v[12:15]
	v_mfma_f32_16x16x32_bf16 v[4:7], v[44:47], v[220:223], v[4:7]
	s_setprio 0
	s_setprio 1
	v_mfma_f32_16x16x32_bf16 v[24:27], v[144:147], v[208:211], v[24:27]
	v_mfma_f32_16x16x32_bf16 v[16:19], v[166:169], v[208:211], v[16:19]
	v_mfma_f32_16x16x32_bf16 v[8:11], v[144:147], v[216:219], v[8:11]
	v_mfma_f32_16x16x32_bf16 v[0:3], v[166:169], v[216:219], v[0:3]
	v_mfma_f32_16x16x32_bf16 v[28:31], v[144:147], v[192:195], v[72:75]
	v_mfma_f32_16x16x32_bf16 v[32:35], v[166:169], v[192:195], v[64:67]
	v_mfma_f32_16x16x32_bf16 v[40:43], v[144:147], v[200:203], v[56:59]
	v_mfma_f32_16x16x32_bf16 v[44:47], v[166:169], v[200:203], v[48:51]
	v_mfma_f32_16x16x32_bf16 v[24:27], v[148:151], v[212:215], v[24:27]
	v_mfma_f32_16x16x32_bf16 v[16:19], v[188:191], v[212:215], v[16:19]
	v_mfma_f32_16x16x32_bf16 v[8:11], v[148:151], v[220:223], v[8:11]
	v_mfma_f32_16x16x32_bf16 v[0:3], v[188:191], v[220:223], v[0:3]
	v_mfma_f32_16x16x32_bf16 v[28:31], v[148:151], v[196:199], v[28:31]
	v_mfma_f32_16x16x32_bf16 v[32:35], v[188:191], v[196:199], v[32:35]
	v_mfma_f32_16x16x32_bf16 v[40:43], v[148:151], v[204:207], v[40:43]
	v_mfma_f32_16x16x32_bf16 v[44:47], v[188:191], v[204:207], v[44:47]
	s_setprio 0
	s_barrier
	v_add_u32_e32 v72, vcc_lo, v171
	v_add_u32_e32 v187, s57, v171
	ds_read_b128 v[48:51], v72
	ds_read_b128 v[56:59], v72 offset:1024
	ds_read_b128 v[64:67], v72 offset:2048
	ds_read_b128 v[72:75], v72 offset:3072
	ds_read_b128 v[144:147], v187
	ds_read_b128 v[148:151], v187 offset:1024
	ds_read_b128 v[166:169], v187 offset:2048
	ds_read_b128 v[188:191], v187 offset:3072
	s_mov_b32 m0, s79
	v_lshl_add_u64 v[232:233], s[38:39], 0, v[160:161]
	ds_read_b128 v[192:195], v175 offset:32768
	ds_read_b128 v[196:199], v175 offset:33792
	ds_read_b128 v[200:203], v175 offset:34816
	ds_read_b128 v[204:207], v175 offset:35840
	ds_read_b128 v[208:211], v175 offset:36864
	ds_read_b128 v[212:215], v175 offset:37888
	ds_read_b128 v[216:219], v175 offset:38912
	ds_read_b128 v[220:223], v175 offset:39936
	global_load_lds_dwordx4 v[232:233], off
	v_lshl_add_u64 v[232:233], s[38:39], 0, v[156:157]
	s_mov_b32 m0, s86
	s_nop 0
	global_load_lds_dwordx4 v[232:233], off
	s_waitcnt vmcnt(8)
	s_cmp_eq_u32 s99, 0
	s_cbranch_scc1 .Ldp_1_l
	v_readlane_b32 s100, v0, 0
	s_mov_b64 exec, 1
	v_writelane_b32 v0, 1, 0
	s_nop 1
	global_atomic_add v0, v0, s[98:99]
	s_nop 1
	v_writelane_b32 v0, s100, 0
	s_mov_b64 exec, -1
	s_mov_b32 s99, 0
	s_mov_b32 s100, 0

.LBB0_464:
	s_or_b64 exec, exec, s[36:37]
	s_andn2_b64 vcc, exec, s[44:45]
	s_mov_b64 s[0:1], -1
	s_cbranch_vccnz .LBB0_454
	v_readlane_b32 s0, v254, 58
	v_readlane_b32 s1, v254, 59
	s_andn2_b64 vcc, exec, s[0:1]
	s_cbranch_vccnz .LBB0_453
	s_mov_b32 s100, 1
	s_branch .LBB0_453

.Ldpw_2_1b:
	s_waitcnt lgkmcnt(0)
	s_barrier
	s_setprio 1
	s_waitcnt lgkmcnt(0)
	v_mfma_f32_16x16x32_bf16 v[60:63], v[142:145], v[192:195], v[60:63]
	v_mfma_f32_16x16x32_bf16 v[56:59], v[158:161], v[192:195], v[56:59]
	v_mfma_f32_16x16x32_bf16 v[44:47], v[142:145], v[200:203], v[44:47]
	v_mfma_f32_16x16x32_bf16 v[40:43], v[158:161], v[200:203], v[40:43]
	v_mfma_f32_16x16x32_bf16 v[28:31], v[142:145], v[208:211], v[28:31]
	v_mfma_f32_16x16x32_bf16 v[24:27], v[158:161], v[208:211], v[24:27]
	v_mfma_f32_16x16x32_bf16 v[12:15], v[142:145], v[216:219], v[12:15]
	v_mfma_f32_16x16x32_bf16 v[8:11], v[158:161], v[216:219], v[8:11]
	v_mfma_f32_16x16x32_bf16 v[60:63], v[154:157], v[196:199], v[60:63]
	v_mfma_f32_16x16x32_bf16 v[56:59], v[162:165], v[196:199], v[56:59]
	v_mfma_f32_16x16x32_bf16 v[44:47], v[154:157], v[204:207], v[44:47]
	v_mfma_f32_16x16x32_bf16 v[40:43], v[162:165], v[204:207], v[40:43]
	v_mfma_f32_16x16x32_bf16 v[28:31], v[154:157], v[212:215], v[28:31]
	v_mfma_f32_16x16x32_bf16 v[24:27], v[162:165], v[212:215], v[24:27]
	v_mfma_f32_16x16x32_bf16 v[12:15], v[154:157], v[220:223], v[12:15]
	v_mfma_f32_16x16x32_bf16 v[8:11], v[162:165], v[220:223], v[8:11]
	s_setprio 0
	s_setprio 1
	v_mfma_f32_16x16x32_bf16 v[52:55], v[166:169], v[192:195], v[52:55]
	v_mfma_f32_16x16x32_bf16 v[48:51], v[184:187], v[192:195], v[48:51]
	v_mfma_f32_16x16x32_bf16 v[36:39], v[166:169], v[200:203], v[36:39]
	v_mfma_f32_16x16x32_bf16 v[32:35], v[184:187], v[200:203], v[32:35]
	v_mfma_f32_16x16x32_bf16 v[20:23], v[166:169], v[208:211], v[20:23]
	v_mfma_f32_16x16x32_bf16 v[16:19], v[184:187], v[208:211], v[16:19]
	v_mfma_f32_16x16x32_bf16 v[4:7], v[166:169], v[216:219], v[4:7]
	v_mfma_f32_16x16x32_bf16 v[0:3], v[184:187], v[216:219], v[0:3]
	v_mfma_f32_16x16x32_bf16 v[52:55], v[170:173], v[196:199], v[52:55]
	v_mfma_f32_16x16x32_bf16 v[48:51], v[188:191], v[196:199], v[48:51]
	v_mfma_f32_16x16x32_bf16 v[36:39], v[170:173], v[204:207], v[36:39]
	v_mfma_f32_16x16x32_bf16 v[32:35], v[188:191], v[204:207], v[32:35]
	v_mfma_f32_16x16x32_bf16 v[20:23], v[170:173], v[212:215], v[20:23]
	v_mfma_f32_16x16x32_bf16 v[16:19], v[188:191], v[212:215], v[16:19]
	v_mfma_f32_16x16x32_bf16 v[4:7], v[170:173], v[220:223], v[4:7]
	v_mfma_f32_16x16x32_bf16 v[0:3], v[188:191], v[220:223], v[0:3]
	s_setprio 0
	s_barrier
	s_add_i32 s87, 0, 0x18000
	v_add_u32_e32 v151, s87, v147
	s_add_i32 s88, 0, 0x1c000
	ds_read_b128 v[142:145], v151
	ds_read_b128 v[154:157], v151 offset:1024
	ds_read_b128 v[158:161], v151 offset:2048
	ds_read_b128 v[162:165], v151 offset:3072
	v_add_u32_e32 v151, s88, v147
	ds_read_b128 v[166:169], v151
	ds_read_b128 v[170:173], v151 offset:1024
	ds_read_b128 v[184:187], v151 offset:2048
	ds_read_b128 v[188:191], v151 offset:3072
	s_add_u32 s18, s36, 0x40000
	s_addc_u32 s19, s37, 0
	s_mov_b32 m0, s28
	v_lshl_add_u64 v[230:231], s[18:19], 0, v[128:129]
	ds_read_b128 v[192:195], v150 offset:32768
	ds_read_b128 v[196:199], v150 offset:33792
	ds_read_b128 v[200:203], v150 offset:34816
	ds_read_b128 v[204:207], v150 offset:35840
	ds_read_b128 v[208:211], v150 offset:36864
	ds_read_b128 v[212:215], v150 offset:37888
	ds_read_b128 v[216:219], v150 offset:38912
	ds_read_b128 v[220:223], v150 offset:39936
	global_load_lds_dwordx4 v[230:231], off
	v_lshl_add_u64 v[230:231], s[18:19], 0, v[132:133]
	s_mov_b32 m0, s29
	s_nop 0
	global_load_lds_dwordx4 v[230:231], off
	s_waitcnt vmcnt(8)
	s_cmp_eq_u32 s99, 0
	s_cbranch_scc1 .Ldp_2_l
	v_readlane_b32 s100, v0, 0
	s_mov_b64 exec, 1
	v_writelane_b32 v0, 1, 0
	s_nop 1
	global_atomic_add v0, v0, s[98:99]
	s_nop 1
	v_writelane_b32 v0, s100, 0
	s_mov_b64 exec, -1
	s_mov_b32 s99, 0
	s_mov_b32 s100, 0

.Ldpw_3_1b:
	s_waitcnt lgkmcnt(0)
	s_barrier
	s_setprio 1
	s_waitcnt lgkmcnt(0)
	v_mfma_f32_16x16x32_bf16 v[60:63], v[142:145], v[188:191], v[60:63]
	v_mfma_f32_16x16x32_bf16 v[56:59], v[154:157], v[188:191], v[56:59]
	v_mfma_f32_16x16x32_bf16 v[44:47], v[142:145], v[196:199], v[44:47]
	v_mfma_f32_16x16x32_bf16 v[40:43], v[154:157], v[196:199], v[40:43]
	v_mfma_f32_16x16x32_bf16 v[28:31], v[142:145], v[204:207], v[28:31]
	v_mfma_f32_16x16x32_bf16 v[24:27], v[154:157], v[204:207], v[24:27]
	v_mfma_f32_16x16x32_bf16 v[12:15], v[142:145], v[212:215], v[12:15]
	v_mfma_f32_16x16x32_bf16 v[8:11], v[154:157], v[212:215], v[8:11]
	v_mfma_f32_16x16x32_bf16 v[60:63], v[146:149], v[192:195], v[60:63]
	v_mfma_f32_16x16x32_bf16 v[56:59], v[158:161], v[192:195], v[56:59]
	v_mfma_f32_16x16x32_bf16 v[44:47], v[146:149], v[200:203], v[44:47]
	v_mfma_f32_16x16x32_bf16 v[40:43], v[158:161], v[200:203], v[40:43]
	v_mfma_f32_16x16x32_bf16 v[28:31], v[146:149], v[208:211], v[28:31]
	v_mfma_f32_16x16x32_bf16 v[24:27], v[158:161], v[208:211], v[24:27]
	v_mfma_f32_16x16x32_bf16 v[12:15], v[146:149], v[216:219], v[12:15]
	v_mfma_f32_16x16x32_bf16 v[8:11], v[158:161], v[216:219], v[8:11]
	s_setprio 0
	s_setprio 1
	v_mfma_f32_16x16x32_bf16 v[52:55], v[162:165], v[188:191], v[52:55]
	v_mfma_f32_16x16x32_bf16 v[48:51], v[170:173], v[188:191], v[48:51]
	v_mfma_f32_16x16x32_bf16 v[36:39], v[162:165], v[196:199], v[36:39]
	v_mfma_f32_16x16x32_bf16 v[32:35], v[170:173], v[196:199], v[32:35]
	v_mfma_f32_16x16x32_bf16 v[20:23], v[162:165], v[204:207], v[20:23]
	v_mfma_f32_16x16x32_bf16 v[16:19], v[170:173], v[204:207], v[16:19]
	v_mfma_f32_16x16x32_bf16 v[4:7], v[162:165], v[212:215], v[4:7]
	v_mfma_f32_16x16x32_bf16 v[0:3], v[170:173], v[212:215], v[0:3]
	v_mfma_f32_16x16x32_bf16 v[52:55], v[166:169], v[192:195], v[52:55]
	v_mfma_f32_16x16x32_bf16 v[48:51], v[184:187], v[192:195], v[48:51]
	v_mfma_f32_16x16x32_bf16 v[36:39], v[166:169], v[200:203], v[36:39]
	v_mfma_f32_16x16x32_bf16 v[32:35], v[184:187], v[200:203], v[32:35]
	v_mfma_f32_16x16x32_bf16 v[20:23], v[166:169], v[208:211], v[20:23]
	v_mfma_f32_16x16x32_bf16 v[16:19], v[184:187], v[208:211], v[16:19]
	v_mfma_f32_16x16x32_bf16 v[4:7], v[166:169], v[216:219], v[4:7]
	v_mfma_f32_16x16x32_bf16 v[0:3], v[184:187], v[216:219], v[0:3]
	s_setprio 0
	s_barrier
	s_add_i32 s18, 0, 0x18000
	v_add_u32_e32 v141, s18, v138
	s_add_i32 s19, 0, 0x1c000
	ds_read_b128 v[142:145], v141
	ds_read_b128 v[146:149], v141 offset:1024
	ds_read_b128 v[154:157], v141 offset:2048
	ds_read_b128 v[158:161], v141 offset:3072
	v_add_u32_e32 v141, s19, v138
	ds_read_b128 v[162:165], v141
	ds_read_b128 v[166:169], v141 offset:1024
	ds_read_b128 v[170:173], v141 offset:2048
	ds_read_b128 v[184:187], v141 offset:3072
	s_add_u32 s8, s8, 0x40000
	s_addc_u32 s9, s9, 0
	s_mov_b32 m0, s33
	v_lshl_add_u64 v[224:225], s[8:9], 0, v[128:129]
	ds_read_b128 v[188:191], v140 offset:32768
	ds_read_b128 v[192:195], v140 offset:33792
	ds_read_b128 v[196:199], v140 offset:34816
	ds_read_b128 v[200:203], v140 offset:35840
	ds_read_b128 v[204:207], v140 offset:36864
	ds_read_b128 v[208:211], v140 offset:37888
	ds_read_b128 v[212:215], v140 offset:38912
	ds_read_b128 v[216:219], v140 offset:39936
	global_load_lds_dwordx4 v[224:225], off
	v_lshl_add_u64 v[224:225], s[8:9], 0, v[132:133]
	s_mov_b32 m0, s36
	s_nop 0
	global_load_lds_dwordx4 v[224:225], off
	s_waitcnt vmcnt(8)
	s_cmp_eq_u32 s99, 0
	s_cbranch_scc1 .Ldp_3_l
	v_readlane_b32 s100, v0, 0
	s_mov_b64 exec, 1
	v_writelane_b32 v0, 1, 0
	s_nop 1
	global_atomic_add v0, v0, s[98:99]
	s_nop 1
	v_writelane_b32 v0, s100, 0
	s_mov_b64 exec, -1
	s_mov_b32 s99, 0
	s_mov_b32 s100, 0

.LBB0_1113:
	s_ashr_i32 s71, s70, 31
	s_lshl_b64 s[6:7], s[70:71], 19
	s_add_u32 s72, s30, s6
	s_addc_u32 s73, s31, s7
	s_and_b64 s[6:7], s[12:13], exec
	s_cselect_b32 s16, s73, s81
	s_cselect_b32 s17, s72, s80
	s_ashr_i32 s69, s68, 31
	s_lshl_b64 s[6:7], s[68:69], 19
	v_readlane_b32 s8, v254, 44
	s_add_u32 s74, s8, s6
	v_readlane_b32 s6, v254, 46
	s_addc_u32 s75, s6, s7
	s_and_b64 s[6:7], s[12:13], exec
	s_cselect_b32 s55, s75, s83
	s_cselect_b32 s63, s74, s82
	s_add_u32 s69, s80, 0x40000
	s_addc_u32 s71, s81, 0
	s_lshl_b32 s6, s70, 6
	s_ashr_i32 s7, s6, 31
	s_cmpk_lt_i32 s70, 0x42
	s_cselect_b32 s42, 8, 4
	s_lshl_b64 s[6:7], s[6:7], 2
	v_readlane_b32 s8, v255, 2
	s_add_u32 s84, s8, s6
	v_readlane_b32 s6, v255, 3
	v_mov_b32_e32 v0, 0
	s_addc_u32 s85, s6, s7
	s_mov_b32 s43, 0
	v_mov_b32_e32 v156, 0
	v_mov_b32_e32 v157, 0
	v_mov_b32_e32 v158, 0
	v_mov_b32_e32 v159, 0
	s_nop 1
	v_mfma_f32_32x32x16_bf16 v[0:15], v[156:159], v[156:159], 0
	v_mfma_f32_32x32x16_bf16 v[16:31], v[156:159], v[156:159], 0
	v_mfma_f32_32x32x16_bf16 v[32:47], v[156:159], v[156:159], 0
	v_mfma_f32_32x32x16_bf16 v[48:63], v[156:159], v[156:159], 0
	v_mfma_f32_32x32x16_bf16 v[64:79], v[156:159], v[156:159], 0
	v_mfma_f32_32x32x16_bf16 v[80:95], v[156:159], v[156:159], 0
	v_mfma_f32_32x32x16_bf16 v[96:111], v[156:159], v[156:159], 0
	v_mfma_f32_32x32x16_bf16 v[112:127], v[156:159], v[156:159], 0
	s_cmp_eq_u32 s100, 1
	s_cbranch_scc0 .Lbm_GU
	s_mov_b32 s100, 0
	s_barrier
.Lbm_GU:
	s_branch .LBB0_1117
.LBB0_1114:
	s_waitcnt lgkmcnt(0)
	buffer_inv sc1
	s_waitcnt vmcnt(0)

.Ldpw_4_1b:
	s_waitcnt lgkmcnt(0)
	s_barrier
	s_setprio 1
	s_waitcnt lgkmcnt(0)
	v_mfma_f32_16x16x32_bf16 v[60:63], v[156:159], v[188:191], v[60:63]
	v_mfma_f32_16x16x32_bf16 v[56:59], v[164:167], v[188:191], v[56:59]
	v_mfma_f32_16x16x32_bf16 v[44:47], v[156:159], v[196:199], v[44:47]
	v_mfma_f32_16x16x32_bf16 v[40:43], v[164:167], v[196:199], v[40:43]
	v_mfma_f32_16x16x32_bf16 v[28:31], v[156:159], v[204:207], v[28:31]
	v_mfma_f32_16x16x32_bf16 v[24:27], v[164:167], v[204:207], v[24:27]
	v_mfma_f32_16x16x32_bf16 v[12:15], v[156:159], v[212:215], v[12:15]
	v_mfma_f32_16x16x32_bf16 v[8:11], v[164:167], v[212:215], v[8:11]
	v_mfma_f32_16x16x32_bf16 v[60:63], v[160:163], v[192:195], v[60:63]
	v_mfma_f32_16x16x32_bf16 v[56:59], v[168:171], v[192:195], v[56:59]
	v_mfma_f32_16x16x32_bf16 v[44:47], v[160:163], v[200:203], v[44:47]
	v_mfma_f32_16x16x32_bf16 v[40:43], v[168:171], v[200:203], v[40:43]
	v_mfma_f32_16x16x32_bf16 v[28:31], v[160:163], v[208:211], v[28:31]
	v_mfma_f32_16x16x32_bf16 v[24:27], v[168:171], v[208:211], v[24:27]
	v_mfma_f32_16x16x32_bf16 v[12:15], v[160:163], v[216:219], v[12:15]
	v_mfma_f32_16x16x32_bf16 v[8:11], v[168:171], v[216:219], v[8:11]
	s_setprio 0
	s_setprio 1
	v_mfma_f32_16x16x32_bf16 v[52:55], v[172:175], v[188:191], v[52:55]
	v_mfma_f32_16x16x32_bf16 v[48:51], v[180:183], v[188:191], v[48:51]
	v_mfma_f32_16x16x32_bf16 v[36:39], v[172:175], v[196:199], v[36:39]
	v_mfma_f32_16x16x32_bf16 v[32:35], v[180:183], v[196:199], v[32:35]
	v_mfma_f32_16x16x32_bf16 v[20:23], v[172:175], v[204:207], v[20:23]
	v_mfma_f32_16x16x32_bf16 v[16:19], v[180:183], v[204:207], v[16:19]
	v_mfma_f32_16x16x32_bf16 v[4:7], v[172:175], v[212:215], v[4:7]
	v_mfma_f32_16x16x32_bf16 v[0:3], v[180:183], v[212:215], v[0:3]
	v_mfma_f32_16x16x32_bf16 v[52:55], v[176:179], v[192:195], v[52:55]
	v_mfma_f32_16x16x32_bf16 v[48:51], v[184:187], v[192:195], v[48:51]
	v_mfma_f32_16x16x32_bf16 v[36:39], v[176:179], v[200:203], v[36:39]
	v_mfma_f32_16x16x32_bf16 v[32:35], v[184:187], v[200:203], v[32:35]
	v_mfma_f32_16x16x32_bf16 v[20:23], v[176:179], v[208:211], v[20:23]
	v_mfma_f32_16x16x32_bf16 v[16:19], v[184:187], v[208:211], v[16:19]
	v_mfma_f32_16x16x32_bf16 v[4:7], v[176:179], v[216:219], v[4:7]
	v_mfma_f32_16x16x32_bf16 v[0:3], v[184:187], v[216:219], v[0:3]
	s_setprio 0
	s_barrier
	s_add_i32 s10, 0, 0x18000
	v_add_u32_e32 v147, s10, v145
	s_add_i32 s11, 0, 0x1c000
	ds_read_b128 v[156:159], v147
	ds_read_b128 v[160:163], v147 offset:1024
	ds_read_b128 v[164:167], v147 offset:2048
	ds_read_b128 v[168:171], v147 offset:3072
	v_add_u32_e32 v147, s11, v145
	ds_read_b128 v[172:175], v147
	ds_read_b128 v[176:179], v147 offset:1024
	ds_read_b128 v[180:183], v147 offset:2048
	ds_read_b128 v[184:187], v147 offset:3072
	s_add_u32 s8, s8, 0x40000
	s_addc_u32 s9, s9, 0
	s_mov_b32 m0, s48
	v_lshl_add_u64 v[226:227], s[8:9], 0, v[128:129]
	ds_read_b128 v[188:191], v146 offset:32768
	ds_read_b128 v[192:195], v146 offset:33792
	ds_read_b128 v[196:199], v146 offset:34816
	ds_read_b128 v[200:203], v146 offset:35840
	ds_read_b128 v[204:207], v146 offset:36864
	ds_read_b128 v[208:211], v146 offset:37888
	ds_read_b128 v[212:215], v146 offset:38912
	ds_read_b128 v[216:219], v146 offset:39936
	global_load_lds_dwordx4 v[226:227], off
	v_lshl_add_u64 v[226:227], s[8:9], 0, v[132:133]
	s_mov_b32 m0, s49
	s_nop 0
	global_load_lds_dwordx4 v[226:227], off
	s_waitcnt vmcnt(8)
	s_cmp_eq_u32 s99, 0
	s_cbranch_scc1 .Ldp_4_l
	v_readlane_b32 s100, v0, 0
	s_mov_b64 exec, 1
	v_writelane_b32 v0, 1, 0
	s_nop 1
	global_atomic_add v0, v0, s[98:99]
	s_nop 1
	v_writelane_b32 v0, s100, 0
	s_mov_b64 exec, -1
	s_mov_b32 s99, 0
	s_mov_b32 s100, 0

.LBB0_1191:
	s_or_b64 exec, exec, s[6:7]
	s_andn2_b64 vcc, exec, s[12:13]
	s_mov_b64 s[6:7], -1
	s_cbranch_vccnz .LBB0_1106
	v_readlane_b32 s6, v255, 7
	v_readlane_b32 s7, v255, 8
	s_andn2_b64 vcc, exec, s[6:7]
	s_cbranch_vccnz .LBB0_1105
	s_mov_b32 s100, 1
	s_branch .LBB0_1105

.Ldpw_5_1b:
	s_waitcnt lgkmcnt(0)
	s_barrier
	s_setprio 1
	s_waitcnt lgkmcnt(0)
	v_mfma_f32_16x16x32_bf16 v[60:63], v[142:145], v[186:189], v[60:63]
	v_mfma_f32_16x16x32_bf16 v[56:59], v[162:165], v[186:189], v[56:59]
	v_mfma_f32_16x16x32_bf16 v[44:47], v[142:145], v[194:197], v[44:47]
	v_mfma_f32_16x16x32_bf16 v[40:43], v[162:165], v[194:197], v[40:43]
	v_mfma_f32_16x16x32_bf16 v[28:31], v[142:145], v[202:205], v[28:31]
	v_mfma_f32_16x16x32_bf16 v[24:27], v[162:165], v[202:205], v[24:27]
	v_mfma_f32_16x16x32_bf16 v[12:15], v[142:145], v[210:213], v[12:15]
	v_mfma_f32_16x16x32_bf16 v[8:11], v[162:165], v[210:213], v[8:11]
	v_mfma_f32_16x16x32_bf16 v[60:63], v[158:161], v[190:193], v[60:63]
	v_mfma_f32_16x16x32_bf16 v[56:59], v[166:169], v[190:193], v[56:59]
	v_mfma_f32_16x16x32_bf16 v[44:47], v[158:161], v[198:201], v[44:47]
	v_mfma_f32_16x16x32_bf16 v[40:43], v[166:169], v[198:201], v[40:43]
	v_mfma_f32_16x16x32_bf16 v[28:31], v[158:161], v[206:209], v[28:31]
	v_mfma_f32_16x16x32_bf16 v[24:27], v[166:169], v[206:209], v[24:27]
	v_mfma_f32_16x16x32_bf16 v[12:15], v[158:161], v[214:217], v[12:15]
	v_mfma_f32_16x16x32_bf16 v[8:11], v[166:169], v[214:217], v[8:11]
	s_setprio 0
	s_setprio 1
	v_mfma_f32_16x16x32_bf16 v[52:55], v[170:173], v[186:189], v[52:55]
	v_mfma_f32_16x16x32_bf16 v[48:51], v[178:181], v[186:189], v[48:51]
	v_mfma_f32_16x16x32_bf16 v[36:39], v[170:173], v[194:197], v[36:39]
	v_mfma_f32_16x16x32_bf16 v[32:35], v[178:181], v[194:197], v[32:35]
	v_mfma_f32_16x16x32_bf16 v[20:23], v[170:173], v[202:205], v[20:23]
	v_mfma_f32_16x16x32_bf16 v[16:19], v[178:181], v[202:205], v[16:19]
	v_mfma_f32_16x16x32_bf16 v[4:7], v[170:173], v[210:213], v[4:7]
	v_mfma_f32_16x16x32_bf16 v[0:3], v[178:181], v[210:213], v[0:3]
	v_mfma_f32_16x16x32_bf16 v[52:55], v[174:177], v[190:193], v[52:55]
	v_mfma_f32_16x16x32_bf16 v[48:51], v[182:185], v[190:193], v[48:51]
	v_mfma_f32_16x16x32_bf16 v[36:39], v[174:177], v[198:201], v[36:39]
	v_mfma_f32_16x16x32_bf16 v[32:35], v[182:185], v[198:201], v[32:35]
	v_mfma_f32_16x16x32_bf16 v[20:23], v[174:177], v[206:209], v[20:23]
	v_mfma_f32_16x16x32_bf16 v[16:19], v[182:185], v[206:209], v[16:19]
	v_mfma_f32_16x16x32_bf16 v[4:7], v[174:177], v[214:217], v[4:7]
	v_mfma_f32_16x16x32_bf16 v[0:3], v[182:185], v[214:217], v[0:3]
	s_setprio 0
	s_barrier
	s_add_i32 s18, 0, 0x18000
	v_add_u32_e32 v157, s18, v147
	s_add_i32 s19, 0, 0x1c000
	ds_read_b128 v[142:145], v157
	ds_read_b128 v[158:161], v157 offset:1024
	ds_read_b128 v[162:165], v157 offset:2048
	ds_read_b128 v[166:169], v157 offset:3072
	v_add_u32_e32 v157, s19, v147
	ds_read_b128 v[170:173], v157
	ds_read_b128 v[174:177], v157 offset:1024
	ds_read_b128 v[178:181], v157 offset:2048
	ds_read_b128 v[182:185], v157 offset:3072
	s_add_u32 s8, s8, 0xb0000
	s_addc_u32 s9, s9, 0
	s_mov_b32 m0, s28
	v_lshl_add_u64 v[226:227], s[8:9], 0, v[128:129]
	ds_read_b128 v[186:189], v156 offset:32768
	ds_read_b128 v[190:193], v156 offset:33792
	ds_read_b128 v[194:197], v156 offset:34816
	ds_read_b128 v[198:201], v156 offset:35840
	ds_read_b128 v[202:205], v156 offset:36864
	ds_read_b128 v[206:209], v156 offset:37888
	ds_read_b128 v[210:213], v156 offset:38912
	ds_read_b128 v[214:217], v156 offset:39936
	global_load_lds_dwordx4 v[226:227], off
	v_lshl_add_u64 v[226:227], s[8:9], 0, v[132:133]
	s_mov_b32 m0, s29
	s_nop 0
	global_load_lds_dwordx4 v[226:227], off
	s_waitcnt vmcnt(8)
	s_cmp_eq_u32 s99, 0
	s_cbranch_scc1 .Ldp_5_l
	v_readlane_b32 s100, v0, 0
	s_mov_b64 exec, 1
	v_writelane_b32 v0, 1, 0
	s_nop 1
	global_atomic_add v0, v0, s[98:99]
	s_nop 1
	v_writelane_b32 v0, s100, 0
	s_mov_b64 exec, -1
	s_mov_b32 s99, 0
	s_mov_b32 s100, 0

.Ldpw_6_1b:
	s_waitcnt lgkmcnt(0)
	s_barrier
	s_setprio 1
	s_waitcnt lgkmcnt(0)
	v_mfma_f32_16x16x32_bf16 v[60:63], v[142:145], v[184:187], v[60:63]
	v_mfma_f32_16x16x32_bf16 v[56:59], v[160:163], v[184:187], v[56:59]
	v_mfma_f32_16x16x32_bf16 v[44:47], v[142:145], v[192:195], v[44:47]
	v_mfma_f32_16x16x32_bf16 v[40:43], v[160:163], v[192:195], v[40:43]
	v_mfma_f32_16x16x32_bf16 v[28:31], v[142:145], v[200:203], v[28:31]
	v_mfma_f32_16x16x32_bf16 v[24:27], v[160:163], v[200:203], v[24:27]
	v_mfma_f32_16x16x32_bf16 v[12:15], v[142:145], v[208:211], v[12:15]
	v_mfma_f32_16x16x32_bf16 v[8:11], v[160:163], v[208:211], v[8:11]
	v_mfma_f32_16x16x32_bf16 v[60:63], v[156:159], v[188:191], v[60:63]
	v_mfma_f32_16x16x32_bf16 v[56:59], v[164:167], v[188:191], v[56:59]
	v_mfma_f32_16x16x32_bf16 v[44:47], v[156:159], v[196:199], v[44:47]
	v_mfma_f32_16x16x32_bf16 v[40:43], v[164:167], v[196:199], v[40:43]
	v_mfma_f32_16x16x32_bf16 v[28:31], v[156:159], v[204:207], v[28:31]
	v_mfma_f32_16x16x32_bf16 v[24:27], v[164:167], v[204:207], v[24:27]
	v_mfma_f32_16x16x32_bf16 v[12:15], v[156:159], v[212:215], v[12:15]
	v_mfma_f32_16x16x32_bf16 v[8:11], v[164:167], v[212:215], v[8:11]
	s_setprio 0
	s_setprio 1
	v_mfma_f32_16x16x32_bf16 v[52:55], v[168:171], v[184:187], v[52:55]
	v_mfma_f32_16x16x32_bf16 v[48:51], v[176:179], v[184:187], v[48:51]
	v_mfma_f32_16x16x32_bf16 v[36:39], v[168:171], v[192:195], v[36:39]
	v_mfma_f32_16x16x32_bf16 v[32:35], v[176:179], v[192:195], v[32:35]
	v_mfma_f32_16x16x32_bf16 v[20:23], v[168:171], v[200:203], v[20:23]
	v_mfma_f32_16x16x32_bf16 v[16:19], v[176:179], v[200:203], v[16:19]
	v_mfma_f32_16x16x32_bf16 v[4:7], v[168:171], v[208:211], v[4:7]
	v_mfma_f32_16x16x32_bf16 v[0:3], v[176:179], v[208:211], v[0:3]
	v_mfma_f32_16x16x32_bf16 v[52:55], v[172:175], v[188:191], v[52:55]
	v_mfma_f32_16x16x32_bf16 v[48:51], v[180:183], v[188:191], v[48:51]
	v_mfma_f32_16x16x32_bf16 v[36:39], v[172:175], v[196:199], v[36:39]
	v_mfma_f32_16x16x32_bf16 v[32:35], v[180:183], v[196:199], v[32:35]
	v_mfma_f32_16x16x32_bf16 v[20:23], v[172:175], v[204:207], v[20:23]
	v_mfma_f32_16x16x32_bf16 v[16:19], v[180:183], v[204:207], v[16:19]
	v_mfma_f32_16x16x32_bf16 v[4:7], v[172:175], v[212:215], v[4:7]
	v_mfma_f32_16x16x32_bf16 v[0:3], v[180:183], v[212:215], v[0:3]
	s_setprio 0
	s_barrier
	s_add_i32 s14, 0, 0x18000
	v_add_u32_e32 v141, s14, v138
	s_add_i32 s18, 0, 0x1c000
	ds_read_b128 v[142:145], v141
	ds_read_b128 v[156:159], v141 offset:1024
	ds_read_b128 v[160:163], v141 offset:2048
	ds_read_b128 v[164:167], v141 offset:3072
	v_add_u32_e32 v141, s18, v138
	ds_read_b128 v[168:171], v141
	ds_read_b128 v[172:175], v141 offset:1024
	ds_read_b128 v[176:179], v141 offset:2048
	ds_read_b128 v[180:183], v141 offset:3072
	s_add_u32 s8, s8, 0xb0000
	s_addc_u32 s9, s9, 0
	s_mov_b32 m0, s27
	v_lshl_add_u64 v[222:223], s[8:9], 0, v[128:129]
	ds_read_b128 v[184:187], v140 offset:32768
	ds_read_b128 v[188:191], v140 offset:33792
	ds_read_b128 v[192:195], v140 offset:34816
	ds_read_b128 v[196:199], v140 offset:35840
	ds_read_b128 v[200:203], v140 offset:36864
	ds_read_b128 v[204:207], v140 offset:37888
	ds_read_b128 v[208:211], v140 offset:38912
	ds_read_b128 v[212:215], v140 offset:39936
	global_load_lds_dwordx4 v[222:223], off
	v_lshl_add_u64 v[222:223], s[8:9], 0, v[132:133]
	s_mov_b32 m0, s28
	s_nop 0
	global_load_lds_dwordx4 v[222:223], off
	s_waitcnt vmcnt(8)
	s_cmp_eq_u32 s99, 0
	s_cbranch_scc1 .Ldp_6_l
	v_readlane_b32 s100, v0, 0
	s_mov_b64 exec, 1
	v_writelane_b32 v0, 1, 0
	s_nop 1
	global_atomic_add v0, v0, s[98:99]
	s_nop 1
	v_writelane_b32 v0, s100, 0
	s_mov_b64 exec, -1
	s_mov_b32 s99, 0
	s_mov_b32 s100, 0

.LBB0_1545:
	s_ashr_i32 s73, s72, 31
	s_lshl_b64 s[6:7], s[72:73], 19
	s_add_u32 s74, s30, s6
	s_addc_u32 s75, s31, s7
	s_and_b64 s[6:7], s[0:1], exec
	s_cselect_b32 s73, s75, s81
	s_cselect_b32 s3, s74, s80
	s_ashr_i32 s71, s70, 31
	s_lshl_b64 s[6:7], s[70:71], 19
	v_readlane_b32 s8, v254, 49
	v_readlane_b32 s9, v254, 50
	s_add_u32 s78, s8, s6
	s_addc_u32 s79, s9, s7
	s_and_b64 s[6:7], s[0:1], exec
	s_cselect_b32 s71, s79, s83
	s_cselect_b32 s33, s78, s82
	s_add_u32 s62, s80, 0x40000
	s_addc_u32 s63, s81, 0
	s_lshl_b32 s6, s72, 6
	s_ashr_i32 s7, s6, 31
	s_cmpk_lt_i32 s72, 0x42
	s_cselect_b32 s42, 8, 4
	s_lshl_b64 s[6:7], s[6:7], 2
	v_readlane_b32 s8, v255, 2
	s_add_u32 s84, s8, s6
	v_readlane_b32 s6, v255, 3
	v_mov_b32_e32 v0, 0
	s_addc_u32 s85, s6, s7
	s_mov_b32 s43, 0
	v_mov_b32_e32 v144, 0
	v_mov_b32_e32 v145, 0
	v_mov_b32_e32 v146, 0
	v_mov_b32_e32 v147, 0
	s_nop 1
	v_mfma_f32_32x32x16_bf16 v[0:15], v[144:147], v[144:147], 0
	v_mfma_f32_32x32x16_bf16 v[16:31], v[144:147], v[144:147], 0
	v_mfma_f32_32x32x16_bf16 v[32:47], v[144:147], v[144:147], 0
	v_mfma_f32_32x32x16_bf16 v[48:63], v[144:147], v[144:147], 0
	v_mfma_f32_32x32x16_bf16 v[64:79], v[144:147], v[144:147], 0
	v_mfma_f32_32x32x16_bf16 v[80:95], v[144:147], v[144:147], 0
	v_mfma_f32_32x32x16_bf16 v[96:111], v[144:147], v[144:147], 0
	v_mfma_f32_32x32x16_bf16 v[112:127], v[144:147], v[144:147], 0
	s_cmp_eq_u32 s100, 1
	s_cbranch_scc0 .Lbm_sc
	s_mov_b32 s100, 0
	s_barrier
.Lbm_sc:
	s_branch .LBB0_1549
.LBB0_1546:
	s_waitcnt lgkmcnt(0)
	buffer_inv sc1
	s_waitcnt vmcnt(0)

.Ldpw_7_1b:
	s_waitcnt lgkmcnt(0)
	s_barrier
	s_setprio 1
	s_waitcnt lgkmcnt(0)
	v_mfma_f32_16x16x32_bf16 v[60:63], v[144:147], v[186:189], v[60:63]
	v_mfma_f32_16x16x32_bf16 v[56:59], v[162:165], v[186:189], v[56:59]
	v_mfma_f32_16x16x32_bf16 v[48:51], v[144:147], v[194:197], v[48:51]
	v_mfma_f32_16x16x32_bf16 v[40:43], v[162:165], v[194:197], v[40:43]
	v_mfma_f32_16x16x32_bf16 v[32:35], v[144:147], v[202:205], v[32:35]
	v_mfma_f32_16x16x32_bf16 v[24:27], v[162:165], v[202:205], v[24:27]
	v_mfma_f32_16x16x32_bf16 v[16:19], v[144:147], v[210:213], v[16:19]
	v_mfma_f32_16x16x32_bf16 v[8:11], v[162:165], v[210:213], v[8:11]
	v_mfma_f32_16x16x32_bf16 v[60:63], v[158:161], v[190:193], v[60:63]
	v_mfma_f32_16x16x32_bf16 v[56:59], v[166:169], v[190:193], v[56:59]
	v_mfma_f32_16x16x32_bf16 v[48:51], v[158:161], v[198:201], v[48:51]
	v_mfma_f32_16x16x32_bf16 v[40:43], v[166:169], v[198:201], v[40:43]
	v_mfma_f32_16x16x32_bf16 v[32:35], v[158:161], v[206:209], v[32:35]
	v_mfma_f32_16x16x32_bf16 v[24:27], v[166:169], v[206:209], v[24:27]
	v_mfma_f32_16x16x32_bf16 v[16:19], v[158:161], v[214:217], v[16:19]
	v_mfma_f32_16x16x32_bf16 v[8:11], v[166:169], v[214:217], v[8:11]
	s_setprio 0
	s_setprio 1
	v_mfma_f32_16x16x32_bf16 v[52:55], v[170:173], v[186:189], v[52:55]
	v_mfma_f32_16x16x32_bf16 v[44:47], v[178:181], v[186:189], v[44:47]
	v_mfma_f32_16x16x32_bf16 v[36:39], v[170:173], v[194:197], v[36:39]
	v_mfma_f32_16x16x32_bf16 v[28:31], v[178:181], v[194:197], v[28:31]
	v_mfma_f32_16x16x32_bf16 v[20:23], v[170:173], v[202:205], v[20:23]
	v_mfma_f32_16x16x32_bf16 v[12:15], v[178:181], v[202:205], v[12:15]
	v_mfma_f32_16x16x32_bf16 v[4:7], v[170:173], v[210:213], v[4:7]
	v_mfma_f32_16x16x32_bf16 v[0:3], v[178:181], v[210:213], v[0:3]
	v_mfma_f32_16x16x32_bf16 v[52:55], v[174:177], v[190:193], v[52:55]
	v_mfma_f32_16x16x32_bf16 v[44:47], v[182:185], v[190:193], v[44:47]
	v_mfma_f32_16x16x32_bf16 v[36:39], v[174:177], v[198:201], v[36:39]
	v_mfma_f32_16x16x32_bf16 v[28:31], v[182:185], v[198:201], v[28:31]
	v_mfma_f32_16x16x32_bf16 v[20:23], v[174:177], v[206:209], v[20:23]
	v_mfma_f32_16x16x32_bf16 v[12:15], v[182:185], v[206:209], v[12:15]
	v_mfma_f32_16x16x32_bf16 v[4:7], v[174:177], v[214:217], v[4:7]
	v_mfma_f32_16x16x32_bf16 v[0:3], v[182:185], v[214:217], v[0:3]
	s_setprio 0
	s_barrier
	s_add_i32 s10, 0, 0x18000
	v_add_u32_e32 v136, s10, v156
	s_add_i32 s11, 0, 0x1c000
	ds_read_b128 v[144:147], v136
	ds_read_b128 v[158:161], v136 offset:1024
	ds_read_b128 v[162:165], v136 offset:2048
	ds_read_b128 v[166:169], v136 offset:3072
	v_add_u32_e32 v136, s11, v156
	ds_read_b128 v[170:173], v136
	ds_read_b128 v[174:177], v136 offset:1024
	ds_read_b128 v[178:181], v136 offset:2048
	ds_read_b128 v[182:185], v136 offset:3072
	s_add_u32 s8, s8, 0x40000
	s_addc_u32 s9, s9, 0
	s_mov_b32 m0, s12
	v_lshl_add_u64 v[226:227], s[8:9], 0, v[128:129]
	ds_read_b128 v[186:189], v157 offset:32768
	ds_read_b128 v[190:193], v157 offset:33792
	ds_read_b128 v[194:197], v157 offset:34816
	ds_read_b128 v[198:201], v157 offset:35840
	ds_read_b128 v[202:205], v157 offset:36864
	ds_read_b128 v[206:209], v157 offset:37888
	ds_read_b128 v[210:213], v157 offset:38912
	ds_read_b128 v[214:217], v157 offset:39936
	global_load_lds_dwordx4 v[226:227], off
	v_lshl_add_u64 v[226:227], s[8:9], 0, v[132:133]
	s_mov_b32 m0, s13
	s_nop 0
	global_load_lds_dwordx4 v[226:227], off
	s_waitcnt vmcnt(8)
	s_cmp_eq_u32 s99, 0
	s_cbranch_scc1 .Ldp_7_l
	v_readlane_b32 s100, v0, 0
	s_mov_b64 exec, 1
	v_writelane_b32 v0, 1, 0
	s_nop 1
	global_atomic_add v0, v0, s[98:99]
	s_nop 1
	v_writelane_b32 v0, s100, 0
	s_mov_b64 exec, -1
	s_mov_b32 s99, 0
	s_mov_b32 s100, 0

.LBB0_1627:
	s_or_b64 exec, exec, s[6:7]
	s_andn2_b64 vcc, exec, s[0:1]
	s_mov_b64 s[0:1], -1
	s_cbranch_vccnz .LBB0_1538
	v_readlane_b32 s0, v254, 41
	v_readlane_b32 s1, v254, 42
	s_andn2_b64 vcc, exec, s[0:1]
	s_cbranch_vccnz .LBB0_1537
	s_mov_b32 s100, 1
	s_branch .LBB0_1537

.Ldpw_8_1b:
	s_waitcnt lgkmcnt(0)
	s_barrier
	s_setprio 1
	s_waitcnt lgkmcnt(0)
	v_mfma_f32_16x16x32_bf16 v[60:63], v[142:145], v[186:189], v[60:63]
	v_mfma_f32_16x16x32_bf16 v[56:59], v[162:165], v[186:189], v[56:59]
	v_mfma_f32_16x16x32_bf16 v[44:47], v[142:145], v[194:197], v[44:47]
	v_mfma_f32_16x16x32_bf16 v[40:43], v[162:165], v[194:197], v[40:43]
	v_mfma_f32_16x16x32_bf16 v[28:31], v[142:145], v[202:205], v[28:31]
	v_mfma_f32_16x16x32_bf16 v[24:27], v[162:165], v[202:205], v[24:27]
	v_mfma_f32_16x16x32_bf16 v[12:15], v[142:145], v[210:213], v[12:15]
	v_mfma_f32_16x16x32_bf16 v[8:11], v[162:165], v[210:213], v[8:11]
	v_mfma_f32_16x16x32_bf16 v[60:63], v[158:161], v[190:193], v[60:63]
	v_mfma_f32_16x16x32_bf16 v[56:59], v[166:169], v[190:193], v[56:59]
	v_mfma_f32_16x16x32_bf16 v[44:47], v[158:161], v[198:201], v[44:47]
	v_mfma_f32_16x16x32_bf16 v[40:43], v[166:169], v[198:201], v[40:43]
	v_mfma_f32_16x16x32_bf16 v[28:31], v[158:161], v[206:209], v[28:31]
	v_mfma_f32_16x16x32_bf16 v[24:27], v[166:169], v[206:209], v[24:27]
	v_mfma_f32_16x16x32_bf16 v[12:15], v[158:161], v[214:217], v[12:15]
	v_mfma_f32_16x16x32_bf16 v[8:11], v[166:169], v[214:217], v[8:11]
	s_setprio 0
	s_setprio 1
	v_mfma_f32_16x16x32_bf16 v[52:55], v[170:173], v[186:189], v[52:55]
	v_mfma_f32_16x16x32_bf16 v[48:51], v[178:181], v[186:189], v[48:51]
	v_mfma_f32_16x16x32_bf16 v[36:39], v[170:173], v[194:197], v[36:39]
	v_mfma_f32_16x16x32_bf16 v[32:35], v[178:181], v[194:197], v[32:35]
	v_mfma_f32_16x16x32_bf16 v[20:23], v[170:173], v[202:205], v[20:23]
	v_mfma_f32_16x16x32_bf16 v[16:19], v[178:181], v[202:205], v[16:19]
	v_mfma_f32_16x16x32_bf16 v[4:7], v[170:173], v[210:213], v[4:7]
	v_mfma_f32_16x16x32_bf16 v[0:3], v[178:181], v[210:213], v[0:3]
	v_mfma_f32_16x16x32_bf16 v[52:55], v[174:177], v[190:193], v[52:55]
	v_mfma_f32_16x16x32_bf16 v[48:51], v[182:185], v[190:193], v[48:51]
	v_mfma_f32_16x16x32_bf16 v[36:39], v[174:177], v[198:201], v[36:39]
	v_mfma_f32_16x16x32_bf16 v[32:35], v[182:185], v[198:201], v[32:35]
	v_mfma_f32_16x16x32_bf16 v[20:23], v[174:177], v[206:209], v[20:23]
	v_mfma_f32_16x16x32_bf16 v[16:19], v[182:185], v[206:209], v[16:19]
	v_mfma_f32_16x16x32_bf16 v[4:7], v[174:177], v[214:217], v[4:7]
	v_mfma_f32_16x16x32_bf16 v[0:3], v[182:185], v[214:217], v[0:3]
	s_setprio 0
	s_barrier
	s_add_i32 s18, 0, 0x18000
	v_add_u32_e32 v157, s18, v147
	s_add_i32 s19, 0, 0x1c000
	ds_read_b128 v[142:145], v157
	ds_read_b128 v[158:161], v157 offset:1024
	ds_read_b128 v[162:165], v157 offset:2048
	ds_read_b128 v[166:169], v157 offset:3072
	v_add_u32_e32 v157, s19, v147
	ds_read_b128 v[170:173], v157
	ds_read_b128 v[174:177], v157 offset:1024
	ds_read_b128 v[178:181], v157 offset:2048
	ds_read_b128 v[182:185], v157 offset:3072
	s_add_u32 s8, s8, 0x40000
	s_addc_u32 s9, s9, 0
	s_mov_b32 m0, s13
	v_lshl_add_u64 v[226:227], s[8:9], 0, v[128:129]
	ds_read_b128 v[186:189], v156 offset:32768
	ds_read_b128 v[190:193], v156 offset:33792
	ds_read_b128 v[194:197], v156 offset:34816
	ds_read_b128 v[198:201], v156 offset:35840
	ds_read_b128 v[202:205], v156 offset:36864
	ds_read_b128 v[206:209], v156 offset:37888
	ds_read_b128 v[210:213], v156 offset:38912
	ds_read_b128 v[214:217], v156 offset:39936
	global_load_lds_dwordx4 v[226:227], off
	v_lshl_add_u64 v[226:227], s[8:9], 0, v[132:133]
	s_mov_b32 m0, s16
	s_nop 0
	global_load_lds_dwordx4 v[226:227], off
	s_waitcnt vmcnt(8)
	s_cmp_eq_u32 s99, 0
	s_cbranch_scc1 .Ldp_8_l
	v_readlane_b32 s100, v0, 0
	s_mov_b64 exec, 1
	v_writelane_b32 v0, 1, 0
	s_nop 1
	global_atomic_add v0, v0, s[98:99]
	s_nop 1
	v_writelane_b32 v0, s100, 0
	s_mov_b64 exec, -1
	s_mov_b32 s99, 0
	s_mov_b32 s100, 0

.Ldpw_9_1b:
	s_waitcnt lgkmcnt(0)
	s_barrier
	s_setprio 1
	s_waitcnt lgkmcnt(0)
	v_mfma_f32_16x16x32_bf16 v[60:63], v[142:145], v[184:187], v[60:63]
	v_mfma_f32_16x16x32_bf16 v[56:59], v[160:163], v[184:187], v[56:59]
	v_mfma_f32_16x16x32_bf16 v[44:47], v[142:145], v[192:195], v[44:47]
	v_mfma_f32_16x16x32_bf16 v[40:43], v[160:163], v[192:195], v[40:43]
	v_mfma_f32_16x16x32_bf16 v[28:31], v[142:145], v[200:203], v[28:31]
	v_mfma_f32_16x16x32_bf16 v[24:27], v[160:163], v[200:203], v[24:27]
	v_mfma_f32_16x16x32_bf16 v[12:15], v[142:145], v[208:211], v[12:15]
	v_mfma_f32_16x16x32_bf16 v[8:11], v[160:163], v[208:211], v[8:11]
	v_mfma_f32_16x16x32_bf16 v[60:63], v[156:159], v[188:191], v[60:63]
	v_mfma_f32_16x16x32_bf16 v[56:59], v[164:167], v[188:191], v[56:59]
	v_mfma_f32_16x16x32_bf16 v[44:47], v[156:159], v[196:199], v[44:47]
	v_mfma_f32_16x16x32_bf16 v[40:43], v[164:167], v[196:199], v[40:43]
	v_mfma_f32_16x16x32_bf16 v[28:31], v[156:159], v[204:207], v[28:31]
	v_mfma_f32_16x16x32_bf16 v[24:27], v[164:167], v[204:207], v[24:27]
	v_mfma_f32_16x16x32_bf16 v[12:15], v[156:159], v[212:215], v[12:15]
	v_mfma_f32_16x16x32_bf16 v[8:11], v[164:167], v[212:215], v[8:11]
	s_setprio 0
	s_setprio 1
	v_mfma_f32_16x16x32_bf16 v[52:55], v[168:171], v[184:187], v[52:55]
	v_mfma_f32_16x16x32_bf16 v[48:51], v[176:179], v[184:187], v[48:51]
	v_mfma_f32_16x16x32_bf16 v[36:39], v[168:171], v[192:195], v[36:39]
	v_mfma_f32_16x16x32_bf16 v[32:35], v[176:179], v[192:195], v[32:35]
	v_mfma_f32_16x16x32_bf16 v[20:23], v[168:171], v[200:203], v[20:23]
	v_mfma_f32_16x16x32_bf16 v[16:19], v[176:179], v[200:203], v[16:19]
	v_mfma_f32_16x16x32_bf16 v[4:7], v[168:171], v[208:211], v[4:7]
	v_mfma_f32_16x16x32_bf16 v[0:3], v[176:179], v[208:211], v[0:3]
	v_mfma_f32_16x16x32_bf16 v[52:55], v[172:175], v[188:191], v[52:55]
	v_mfma_f32_16x16x32_bf16 v[48:51], v[180:183], v[188:191], v[48:51]
	v_mfma_f32_16x16x32_bf16 v[36:39], v[172:175], v[196:199], v[36:39]
	v_mfma_f32_16x16x32_bf16 v[32:35], v[180:183], v[196:199], v[32:35]
	v_mfma_f32_16x16x32_bf16 v[20:23], v[172:175], v[204:207], v[20:23]
	v_mfma_f32_16x16x32_bf16 v[16:19], v[180:183], v[204:207], v[16:19]
	v_mfma_f32_16x16x32_bf16 v[4:7], v[172:175], v[212:215], v[4:7]
	v_mfma_f32_16x16x32_bf16 v[0:3], v[180:183], v[212:215], v[0:3]
	s_setprio 0
	s_barrier
	s_add_i32 s18, 0, 0x18000
	v_add_u32_e32 v141, s18, v138
	s_add_i32 s19, 0, 0x1c000
	ds_read_b128 v[142:145], v141
	ds_read_b128 v[156:159], v141 offset:1024
	ds_read_b128 v[160:163], v141 offset:2048
	ds_read_b128 v[164:167], v141 offset:3072
	v_add_u32_e32 v141, s19, v138
	ds_read_b128 v[168:171], v141
	ds_read_b128 v[172:175], v141 offset:1024
	ds_read_b128 v[176:179], v141 offset:2048
	ds_read_b128 v[180:183], v141 offset:3072
	s_add_u32 s10, s10, 0x40000
	s_addc_u32 s11, s11, 0
	s_mov_b32 m0, s27
	v_lshl_add_u64 v[222:223], s[10:11], 0, v[128:129]
	ds_read_b128 v[184:187], v140 offset:32768
	ds_read_b128 v[188:191], v140 offset:33792
	ds_read_b128 v[192:195], v140 offset:34816
	ds_read_b128 v[196:199], v140 offset:35840
	ds_read_b128 v[200:203], v140 offset:36864
	ds_read_b128 v[204:207], v140 offset:37888
	ds_read_b128 v[208:211], v140 offset:38912
	ds_read_b128 v[212:215], v140 offset:39936
	global_load_lds_dwordx4 v[222:223], off
	v_lshl_add_u64 v[222:223], s[10:11], 0, v[132:133]
	s_mov_b32 m0, s28
	s_nop 0
	global_load_lds_dwordx4 v[222:223], off
	s_waitcnt vmcnt(8)
	s_cmp_eq_u32 s99, 0
	s_cbranch_scc1 .Ldp_9_l
	v_readlane_b32 s100, v0, 0
	s_mov_b64 exec, 1
	v_writelane_b32 v0, 1, 0
	s_nop 1
	global_atomic_add v0, v0, s[98:99]
	s_nop 1
	v_writelane_b32 v0, s100, 0
	s_mov_b64 exec, -1
	s_mov_b32 s99, 0
	s_mov_b32 s100, 0

.LBB0_2158:
	s_ashr_i32 s57, s56, 31
	s_lshl_b64 s[6:7], s[56:57], 19
	s_add_u32 s58, s30, s6
	s_addc_u32 s59, s31, s7
	s_and_b64 s[6:7], s[8:9], exec
	s_cselect_b32 s1, s59, s63
	s_cselect_b32 s15, s58, s62
	s_ashr_i32 s55, s54, 31
	s_lshl_b64 s[6:7], s[54:55], 19
	s_add_u32 s60, s27, s6
	s_addc_u32 s61, s28, s7
	s_and_b64 s[6:7], s[8:9], exec
	s_cselect_b32 s53, s61, s65
	s_cselect_b32 s55, s60, s64
	s_add_u32 s57, s62, 0x40000
	s_addc_u32 s33, s63, 0
	s_lshl_b32 s6, s56, 6
	s_ashr_i32 s7, s6, 31
	s_cmpk_lt_i32 s56, 0x42
	s_cselect_b32 s42, 8, 4
	s_lshl_b64 s[6:7], s[6:7], 2
	v_readlane_b32 s10, v254, 47
	s_add_u32 s66, s10, s6
	v_readlane_b32 s6, v255, 2
	v_mov_b32_e32 v0, 0
	s_addc_u32 s67, s6, s7
	s_mov_b32 s43, 0
	v_mov_b32_e32 v156, 0
	v_mov_b32_e32 v157, 0
	v_mov_b32_e32 v158, 0
	v_mov_b32_e32 v159, 0
	s_nop 1
	v_mfma_f32_32x32x16_bf16 v[0:15], v[156:159], v[156:159], 0
	v_mfma_f32_32x32x16_bf16 v[16:31], v[156:159], v[156:159], 0
	v_mfma_f32_32x32x16_bf16 v[32:47], v[156:159], v[156:159], 0
	v_mfma_f32_32x32x16_bf16 v[48:63], v[156:159], v[156:159], 0
	v_mfma_f32_32x32x16_bf16 v[64:79], v[156:159], v[156:159], 0
	v_mfma_f32_32x32x16_bf16 v[80:95], v[156:159], v[156:159], 0
	v_mfma_f32_32x32x16_bf16 v[96:111], v[156:159], v[156:159], 0
	v_mfma_f32_32x32x16_bf16 v[112:127], v[156:159], v[156:159], 0
	s_cmp_eq_u32 s100, 1
	s_cbranch_scc0 .Lbm_GU2
	s_mov_b32 s100, 0
	s_barrier
.Lbm_GU2:
	s_branch .LBB0_2162
.LBB0_2159:
	s_waitcnt lgkmcnt(0)
	buffer_inv sc1
	s_waitcnt vmcnt(0)

.Ldpw_10_1b:
	s_waitcnt lgkmcnt(0)
	s_barrier
	s_setprio 1
	s_waitcnt lgkmcnt(0)
	v_mfma_f32_16x16x32_bf16 v[60:63], v[156:159], v[188:191], v[60:63]
	v_mfma_f32_16x16x32_bf16 v[56:59], v[164:167], v[188:191], v[56:59]
	v_mfma_f32_16x16x32_bf16 v[44:47], v[156:159], v[196:199], v[44:47]
	v_mfma_f32_16x16x32_bf16 v[40:43], v[164:167], v[196:199], v[40:43]
	v_mfma_f32_16x16x32_bf16 v[28:31], v[156:159], v[204:207], v[28:31]
	v_mfma_f32_16x16x32_bf16 v[24:27], v[164:167], v[204:207], v[24:27]
	v_mfma_f32_16x16x32_bf16 v[12:15], v[156:159], v[212:215], v[12:15]
	v_mfma_f32_16x16x32_bf16 v[8:11], v[164:167], v[212:215], v[8:11]
	v_mfma_f32_16x16x32_bf16 v[60:63], v[160:163], v[192:195], v[60:63]
	v_mfma_f32_16x16x32_bf16 v[56:59], v[168:171], v[192:195], v[56:59]
	v_mfma_f32_16x16x32_bf16 v[44:47], v[160:163], v[200:203], v[44:47]
	v_mfma_f32_16x16x32_bf16 v[40:43], v[168:171], v[200:203], v[40:43]
	v_mfma_f32_16x16x32_bf16 v[28:31], v[160:163], v[208:211], v[28:31]
	v_mfma_f32_16x16x32_bf16 v[24:27], v[168:171], v[208:211], v[24:27]
	v_mfma_f32_16x16x32_bf16 v[12:15], v[160:163], v[216:219], v[12:15]
	v_mfma_f32_16x16x32_bf16 v[8:11], v[168:171], v[216:219], v[8:11]
	s_setprio 0
	s_setprio 1
	v_mfma_f32_16x16x32_bf16 v[52:55], v[172:175], v[188:191], v[52:55]
	v_mfma_f32_16x16x32_bf16 v[48:51], v[180:183], v[188:191], v[48:51]
	v_mfma_f32_16x16x32_bf16 v[36:39], v[172:175], v[196:199], v[36:39]
	v_mfma_f32_16x16x32_bf16 v[32:35], v[180:183], v[196:199], v[32:35]
	v_mfma_f32_16x16x32_bf16 v[20:23], v[172:175], v[204:207], v[20:23]
	v_mfma_f32_16x16x32_bf16 v[16:19], v[180:183], v[204:207], v[16:19]
	v_mfma_f32_16x16x32_bf16 v[4:7], v[172:175], v[212:215], v[4:7]
	v_mfma_f32_16x16x32_bf16 v[0:3], v[180:183], v[212:215], v[0:3]
	v_mfma_f32_16x16x32_bf16 v[52:55], v[176:179], v[192:195], v[52:55]
	v_mfma_f32_16x16x32_bf16 v[48:51], v[184:187], v[192:195], v[48:51]
	v_mfma_f32_16x16x32_bf16 v[36:39], v[176:179], v[200:203], v[36:39]
	v_mfma_f32_16x16x32_bf16 v[32:35], v[184:187], v[200:203], v[32:35]
	v_mfma_f32_16x16x32_bf16 v[20:23], v[176:179], v[208:211], v[20:23]
	v_mfma_f32_16x16x32_bf16 v[16:19], v[184:187], v[208:211], v[16:19]
	v_mfma_f32_16x16x32_bf16 v[4:7], v[176:179], v[216:219], v[4:7]
	v_mfma_f32_16x16x32_bf16 v[0:3], v[184:187], v[216:219], v[0:3]
	s_setprio 0
	s_barrier
	s_add_i32 s48, 0, 0x18000
	v_add_u32_e32 v147, s48, v145
	s_add_i32 s49, 0, 0x1c000
	ds_read_b128 v[156:159], v147
	ds_read_b128 v[160:163], v147 offset:1024
	ds_read_b128 v[164:167], v147 offset:2048
	ds_read_b128 v[168:171], v147 offset:3072
	v_add_u32_e32 v147, s49, v145
	ds_read_b128 v[172:175], v147
	ds_read_b128 v[176:179], v147 offset:1024
	ds_read_b128 v[180:183], v147 offset:2048
	ds_read_b128 v[184:187], v147 offset:3072
	s_add_u32 s18, s38, 0x40000
	s_addc_u32 s19, s39, 0
	s_mov_b32 m0, s94
	v_lshl_add_u64 v[226:227], s[18:19], 0, v[128:129]
	ds_read_b128 v[188:191], v146 offset:32768
	ds_read_b128 v[192:195], v146 offset:33792
	ds_read_b128 v[196:199], v146 offset:34816
	ds_read_b128 v[200:203], v146 offset:35840
	ds_read_b128 v[204:207], v146 offset:36864
	ds_read_b128 v[208:211], v146 offset:37888
	ds_read_b128 v[212:215], v146 offset:38912
	ds_read_b128 v[216:219], v146 offset:39936
	global_load_lds_dwordx4 v[226:227], off
	v_lshl_add_u64 v[226:227], s[18:19], 0, v[132:133]
	s_mov_b32 m0, s95
	s_nop 0
	global_load_lds_dwordx4 v[226:227], off
	s_waitcnt vmcnt(8)
	s_cmp_eq_u32 s99, 0
	s_cbranch_scc1 .Ldp_10_l
	v_readlane_b32 s100, v0, 0
	s_mov_b64 exec, 1
	v_writelane_b32 v0, 1, 0
	s_nop 1
	global_atomic_add v0, v0, s[98:99]
	s_nop 1
	v_writelane_b32 v0, s100, 0
	s_mov_b64 exec, -1
	s_mov_b32 s99, 0
	s_mov_b32 s100, 0

.LBB0_2236:
	s_or_b64 exec, exec, s[6:7]
	s_andn2_b64 vcc, exec, s[8:9]
	s_mov_b64 s[0:1], -1
	s_cbranch_vccnz .LBB0_2151
	s_andn2_b64 vcc, exec, s[34:35]
	s_cbranch_vccnz .LBB0_2150
	s_mov_b32 s100, 1
	s_branch .LBB0_2150

.Ldpw_11_1b:
	s_waitcnt lgkmcnt(0)
	s_barrier
	s_setprio 1
	s_waitcnt lgkmcnt(0)
	v_mfma_f32_16x16x32_bf16 v[60:63], v[142:145], v[186:189], v[60:63]
	v_mfma_f32_16x16x32_bf16 v[56:59], v[162:165], v[186:189], v[56:59]
	v_mfma_f32_16x16x32_bf16 v[44:47], v[142:145], v[194:197], v[44:47]
	v_mfma_f32_16x16x32_bf16 v[40:43], v[162:165], v[194:197], v[40:43]
	v_mfma_f32_16x16x32_bf16 v[28:31], v[142:145], v[202:205], v[28:31]
	v_mfma_f32_16x16x32_bf16 v[24:27], v[162:165], v[202:205], v[24:27]
	v_mfma_f32_16x16x32_bf16 v[12:15], v[142:145], v[210:213], v[12:15]
	v_mfma_f32_16x16x32_bf16 v[8:11], v[162:165], v[210:213], v[8:11]
	v_mfma_f32_16x16x32_bf16 v[60:63], v[158:161], v[190:193], v[60:63]
	v_mfma_f32_16x16x32_bf16 v[56:59], v[166:169], v[190:193], v[56:59]
	v_mfma_f32_16x16x32_bf16 v[44:47], v[158:161], v[198:201], v[44:47]
	v_mfma_f32_16x16x32_bf16 v[40:43], v[166:169], v[198:201], v[40:43]
	v_mfma_f32_16x16x32_bf16 v[28:31], v[158:161], v[206:209], v[28:31]
	v_mfma_f32_16x16x32_bf16 v[24:27], v[166:169], v[206:209], v[24:27]
	v_mfma_f32_16x16x32_bf16 v[12:15], v[158:161], v[214:217], v[12:15]
	v_mfma_f32_16x16x32_bf16 v[8:11], v[166:169], v[214:217], v[8:11]
	s_setprio 0
	s_setprio 1
	v_mfma_f32_16x16x32_bf16 v[52:55], v[170:173], v[186:189], v[52:55]
	v_mfma_f32_16x16x32_bf16 v[48:51], v[178:181], v[186:189], v[48:51]
	v_mfma_f32_16x16x32_bf16 v[36:39], v[170:173], v[194:197], v[36:39]
	v_mfma_f32_16x16x32_bf16 v[32:35], v[178:181], v[194:197], v[32:35]
	v_mfma_f32_16x16x32_bf16 v[20:23], v[170:173], v[202:205], v[20:23]
	v_mfma_f32_16x16x32_bf16 v[16:19], v[178:181], v[202:205], v[16:19]
	v_mfma_f32_16x16x32_bf16 v[4:7], v[170:173], v[210:213], v[4:7]
	v_mfma_f32_16x16x32_bf16 v[0:3], v[178:181], v[210:213], v[0:3]
	v_mfma_f32_16x16x32_bf16 v[52:55], v[174:177], v[190:193], v[52:55]
	v_mfma_f32_16x16x32_bf16 v[48:51], v[182:185], v[190:193], v[48:51]
	v_mfma_f32_16x16x32_bf16 v[36:39], v[174:177], v[198:201], v[36:39]
	v_mfma_f32_16x16x32_bf16 v[32:35], v[182:185], v[198:201], v[32:35]
	v_mfma_f32_16x16x32_bf16 v[20:23], v[174:177], v[206:209], v[20:23]
	v_mfma_f32_16x16x32_bf16 v[16:19], v[182:185], v[206:209], v[16:19]
	v_mfma_f32_16x16x32_bf16 v[4:7], v[174:177], v[214:217], v[4:7]
	v_mfma_f32_16x16x32_bf16 v[0:3], v[182:185], v[214:217], v[0:3]
	s_setprio 0
	s_barrier
	s_add_i32 s76, 0, 0x18000
	v_add_u32_e32 v157, s76, v147
	s_add_i32 s77, 0, 0x1c000
	ds_read_b128 v[142:145], v157
	ds_read_b128 v[158:161], v157 offset:1024
	ds_read_b128 v[162:165], v157 offset:2048
	ds_read_b128 v[166:169], v157 offset:3072
	v_add_u32_e32 v157, s77, v147
	ds_read_b128 v[170:173], v157
	ds_read_b128 v[174:177], v157 offset:1024
	ds_read_b128 v[178:181], v157 offset:2048
	ds_read_b128 v[182:185], v157 offset:3072
	s_add_u32 s18, s66, 0xb0000
	s_addc_u32 s19, s67, 0
	s_mov_b32 m0, s28
	v_lshl_add_u64 v[226:227], s[18:19], 0, v[128:129]
	ds_read_b128 v[186:189], v156 offset:32768
	ds_read_b128 v[190:193], v156 offset:33792
	ds_read_b128 v[194:197], v156 offset:34816
	ds_read_b128 v[198:201], v156 offset:35840
	ds_read_b128 v[202:205], v156 offset:36864
	ds_read_b128 v[206:209], v156 offset:37888
	ds_read_b128 v[210:213], v156 offset:38912
	ds_read_b128 v[214:217], v156 offset:39936
	global_load_lds_dwordx4 v[226:227], off
	v_lshl_add_u64 v[226:227], s[18:19], 0, v[132:133]
	s_mov_b32 m0, s29
	s_nop 0
	global_load_lds_dwordx4 v[226:227], off
	s_waitcnt vmcnt(8)
	s_cmp_eq_u32 s99, 0
	s_cbranch_scc1 .Ldp_11_l
	v_readlane_b32 s100, v0, 0
	s_mov_b64 exec, 1
	v_writelane_b32 v0, 1, 0
	s_nop 1
	global_atomic_add v0, v0, s[98:99]
	s_nop 1
	v_writelane_b32 v0, s100, 0
	s_mov_b64 exec, -1
	s_mov_b32 s99, 0
	s_mov_b32 s100, 0

.Ldpw_12_1b:
	s_waitcnt lgkmcnt(0)
	s_barrier
	s_setprio 1
	s_waitcnt lgkmcnt(0)
	v_mfma_f32_16x16x32_bf16 v[60:63], v[142:145], v[184:187], v[60:63]
	v_mfma_f32_16x16x32_bf16 v[56:59], v[160:163], v[184:187], v[56:59]
	v_mfma_f32_16x16x32_bf16 v[44:47], v[142:145], v[192:195], v[44:47]
	v_mfma_f32_16x16x32_bf16 v[40:43], v[160:163], v[192:195], v[40:43]
	v_mfma_f32_16x16x32_bf16 v[28:31], v[142:145], v[200:203], v[28:31]
	v_mfma_f32_16x16x32_bf16 v[24:27], v[160:163], v[200:203], v[24:27]
	v_mfma_f32_16x16x32_bf16 v[12:15], v[142:145], v[208:211], v[12:15]
	v_mfma_f32_16x16x32_bf16 v[8:11], v[160:163], v[208:211], v[8:11]
	v_mfma_f32_16x16x32_bf16 v[60:63], v[156:159], v[188:191], v[60:63]
	v_mfma_f32_16x16x32_bf16 v[56:59], v[164:167], v[188:191], v[56:59]
	v_mfma_f32_16x16x32_bf16 v[44:47], v[156:159], v[196:199], v[44:47]
	v_mfma_f32_16x16x32_bf16 v[40:43], v[164:167], v[196:199], v[40:43]
	v_mfma_f32_16x16x32_bf16 v[28:31], v[156:159], v[204:207], v[28:31]
	v_mfma_f32_16x16x32_bf16 v[24:27], v[164:167], v[204:207], v[24:27]
	v_mfma_f32_16x16x32_bf16 v[12:15], v[156:159], v[212:215], v[12:15]
	v_mfma_f32_16x16x32_bf16 v[8:11], v[164:167], v[212:215], v[8:11]
	s_setprio 0
	s_setprio 1
	v_mfma_f32_16x16x32_bf16 v[52:55], v[168:171], v[184:187], v[52:55]
	v_mfma_f32_16x16x32_bf16 v[48:51], v[176:179], v[184:187], v[48:51]
	v_mfma_f32_16x16x32_bf16 v[36:39], v[168:171], v[192:195], v[36:39]
	v_mfma_f32_16x16x32_bf16 v[32:35], v[176:179], v[192:195], v[32:35]
	v_mfma_f32_16x16x32_bf16 v[20:23], v[168:171], v[200:203], v[20:23]
	v_mfma_f32_16x16x32_bf16 v[16:19], v[176:179], v[200:203], v[16:19]
	v_mfma_f32_16x16x32_bf16 v[4:7], v[168:171], v[208:211], v[4:7]
	v_mfma_f32_16x16x32_bf16 v[0:3], v[176:179], v[208:211], v[0:3]
	v_mfma_f32_16x16x32_bf16 v[52:55], v[172:175], v[188:191], v[52:55]
	v_mfma_f32_16x16x32_bf16 v[48:51], v[180:183], v[188:191], v[48:51]
	v_mfma_f32_16x16x32_bf16 v[36:39], v[172:175], v[196:199], v[36:39]
	v_mfma_f32_16x16x32_bf16 v[32:35], v[180:183], v[196:199], v[32:35]
	v_mfma_f32_16x16x32_bf16 v[20:23], v[172:175], v[204:207], v[20:23]
	v_mfma_f32_16x16x32_bf16 v[16:19], v[180:183], v[204:207], v[16:19]
	v_mfma_f32_16x16x32_bf16 v[4:7], v[172:175], v[212:215], v[4:7]
	v_mfma_f32_16x16x32_bf16 v[0:3], v[180:183], v[212:215], v[0:3]
	s_setprio 0
	s_barrier
	s_add_i32 s6, 0, 0x18000
	v_add_u32_e32 v141, s6, v138
	s_add_i32 s43, 0, 0x1c000
	ds_read_b128 v[142:145], v141
	ds_read_b128 v[156:159], v141 offset:1024
	ds_read_b128 v[160:163], v141 offset:2048
	ds_read_b128 v[164:167], v141 offset:3072
	v_add_u32_e32 v141, s43, v138
	ds_read_b128 v[168:171], v141
	ds_read_b128 v[172:175], v141 offset:1024
	ds_read_b128 v[176:179], v141 offset:2048
	ds_read_b128 v[180:183], v141 offset:3072
	s_add_u32 s18, s72, 0xb0000
	s_addc_u32 s19, s73, 0
	s_mov_b32 m0, s75
	v_lshl_add_u64 v[222:223], s[18:19], 0, v[128:129]
	ds_read_b128 v[184:187], v140 offset:32768
	ds_read_b128 v[188:191], v140 offset:33792
	ds_read_b128 v[192:195], v140 offset:34816
	ds_read_b128 v[196:199], v140 offset:35840
	ds_read_b128 v[200:203], v140 offset:36864
	ds_read_b128 v[204:207], v140 offset:37888
	ds_read_b128 v[208:211], v140 offset:38912
	ds_read_b128 v[212:215], v140 offset:39936
	global_load_lds_dwordx4 v[222:223], off
	v_lshl_add_u64 v[222:223], s[18:19], 0, v[132:133]
	s_mov_b32 m0, s76
	s_nop 0
	global_load_lds_dwordx4 v[222:223], off
	s_waitcnt vmcnt(8)
	s_cmp_eq_u32 s99, 0
	s_cbranch_scc1 .Ldp_12_l
	v_readlane_b32 s100, v0, 0
	s_mov_b64 exec, 1
	v_writelane_b32 v0, 1, 0
	s_nop 1
	global_atomic_add v0, v0, s[98:99]
	s_nop 1
	v_writelane_b32 v0, s100, 0
	s_mov_b64 exec, -1
	s_mov_b32 s99, 0
	s_mov_b32 s100, 0
